# grid barrier: non-leader workgroups poll the top-level generation word directly instead of the per-XCD generation word (one atomic + one poll round trip less on the release path)
# speedup vs baseline: 1.0125x; 1.0013x over previous
.LBB0_207:
	s_or_b64 exec, exec, s[12:13]
	v_cvt_f32_u32_e32 v5, v3
	s_waitcnt vmcnt(0)
	v_readfirstlane_b32 s6, v4
	v_sub_u32_e32 v4, 0, v3
	v_rcp_iflag_f32_e32 v5, v5
	v_add_u32_e32 v6, s6, v1
	v_mul_f32_e32 v5, 0x4f7ffffe, v5
	v_cvt_u32_f32_e32 v5, v5
	v_mul_lo_u32 v1, v4, v5
	v_mul_hi_u32 v1, v5, v1
	v_add_u32_e32 v1, v5, v1
	v_mul_hi_u32 v1, v6, v1
	v_mul_lo_u32 v4, v1, v3
	v_sub_u32_e32 v4, v6, v4
	v_add_u32_e32 v5, 1, v1
	v_cmp_ge_u32_e32 vcc, v4, v3
	s_nop 1
	v_cndmask_b32_e32 v1, v1, v5, vcc
	v_sub_u32_e32 v5, v4, v3
	v_cndmask_b32_e32 v4, v4, v5, vcc
	v_add_u32_e32 v5, 1, v1
	v_cmp_ge_u32_e32 vcc, v4, v3
	v_add_u32_e32 v4, 1, v6
	s_nop 0
	v_cndmask_b32_e32 v1, v1, v5, vcc
	v_mul_lo_u32 v5, v3, v1
	v_add_u32_e32 v3, v5, v3
	v_cmp_ne_u32_e32 vcc, v4, v3
	s_and_saveexec_b64 s[12:13], vcc
	s_xor_b64 s[12:13], exec, s[12:13]
	s_cbranch_execz .LBB0_221
	v_readlane_b32 s14, v253, 51
	v_readlane_b32 s15, v253, 52
	s_waitcnt lgkmcnt(0)
	s_nop 3
	global_load_dword v2, v0, s[14:15] sc1
	s_waitcnt vmcnt(0)
	v_cmp_eq_u32_e32 vcc, v2, v1
	s_and_saveexec_b64 s[14:15], vcc
	s_cbranch_execz .LBB0_220
	s_mov_b32 s6, 1
	s_mov_b64 s[26:27], 0
	s_branch .LBB0_211
